# grid barrier before the last layer's out-GEMM made XCD-local (no weight conversion follows it); otherwise as previous best
# baseline (speedup 1.0000x reference)
; __device__ __forceinline__ int my_tid(int wave0) { int l; asm volatile("v_mbcnt_lo_u32_b32 %0, -1, 0\n\tv_mbcnt_hi_u32_b32 %0, -1, %0" : "=&v"(l)); return wave0 * 64 + l; }
; __global__ void __launch_bounds__(NWAVES * 64, 2) fwd(Params p) {
;     ...
;         const int L = id / 6, k = id % 6, j = L >> 1; const bool df = (L & 1) != 0;
;         const bool fusedn = (G == 256);
;         if (k == 2 || (k == 0 && L > 0 && fusedn)) continue;
;         if (id > p.ph_lo) xcd_barrier(bar, my_tid(wave0) == 0);
.LBB0_56:
	s_andn2_saveexec_b64 s[6:7], s[6:7]
	s_cbranch_execz .LBB0_76
	s_mov_b64 s[6:7], exec
	v_readlane_b32 s8, v255, 11
	s_cmp_eq_u32 s8, 3
	s_cselect_b32 s9, 1, 0
	s_cmp_eq_u32 s8, 4
	s_cselect_b32 s9, 1, s9
	v_readlane_b32 s8, v255, 12
	s_cmp_eq_u32 s8, 23
	s_cselect_b32 s9, 1, s9
	s_cmp_eq_u32 s9, 0
	s_cbranch_scc1 .Lxb_global
	v_readlane_b32 s9, v253, 0
	s_cmp_eq_u32 s9, 0
	s_cbranch_scc1 .Lxb_global
	v_mov_b32_e32 v8, 0x20808
	ds_read_b32 v9, v8
	s_waitcnt lgkmcnt(0)
	v_readfirstlane_b32 s8, v9
	s_cmp_lg_u32 s8, 0
	s_cbranch_scc1 .Lxb_have
	v_mov_b32_e32 v8, 0x3800
	global_load_dword v9, v8, s[86:87] offset:0 sc1
	global_load_dword v10, v8, s[86:87] offset:256 sc1
	global_load_dword v11, v8, s[86:87] offset:512 sc1
	global_load_dword v12, v8, s[86:87] offset:768 sc1
	global_load_dword v13, v8, s[86:87] offset:1024 sc1
	global_load_dword v14, v8, s[86:87] offset:1280 sc1
	global_load_dword v15, v8, s[86:87] offset:1536 sc1
	global_load_dword v16, v8, s[86:87] offset:1792 sc1
	s_waitcnt vmcnt(0)
	s_mov_b32 s8, 1
	v_readfirstlane_b32 s9, v9
	s_bcnt1_i32_b32 s9, s9
	s_cmp_eq_u32 s9, 1
	s_cselect_b32 s8, s8, 2
	v_readfirstlane_b32 s9, v10
	s_bcnt1_i32_b32 s9, s9
	s_cmp_eq_u32 s9, 1
	s_cselect_b32 s8, s8, 2
	v_readfirstlane_b32 s9, v11
	s_bcnt1_i32_b32 s9, s9
	s_cmp_eq_u32 s9, 1
	s_cselect_b32 s8, s8, 2
	v_readfirstlane_b32 s9, v12
	s_bcnt1_i32_b32 s9, s9
	s_cmp_eq_u32 s9, 1
	s_cselect_b32 s8, s8, 2
	v_readfirstlane_b32 s9, v13
	s_bcnt1_i32_b32 s9, s9
	s_cmp_eq_u32 s9, 1
	s_cselect_b32 s8, s8, 2
	v_readfirstlane_b32 s9, v14
	s_bcnt1_i32_b32 s9, s9
	s_cmp_eq_u32 s9, 1
	s_cselect_b32 s8, s8, 2
	v_readfirstlane_b32 s9, v15
	s_bcnt1_i32_b32 s9, s9
	s_cmp_eq_u32 s9, 1
	s_cselect_b32 s8, s8, 2
	v_readfirstlane_b32 s9, v16
	s_bcnt1_i32_b32 s9, s9
	s_cmp_eq_u32 s9, 1
	s_cselect_b32 s8, s8, 2
	v_mov_b32_e32 v8, 0x20808
	v_mov_b32_e32 v9, s8
	ds_write_b32 v8, v9
	s_waitcnt lgkmcnt(0)
